# Hyena filter unit on f32 matrix cores (v_mfma_f32_32x32x2_f32, f32 operands and accumulate) instead of f32 VALU MACs fed by broadcast vector loads
# speedup vs baseline: 1.1439x; 1.0348x over previous
; DI int tidx() { int t = __builtin_amdgcn_workitem_id_x(); asm volatile("" : "+v"(t)); return t; }
; DI void filt_unit(KP p, int l, int u) {
;   const int tb = u >> 6, cb = u & 63;
;   const int t = tb * 256 + tidx();
;   const float* hr = (const float*)(p->ws + OFF_HID) + ((size_t)l * 4096 + t) * 64;
;   const float* wout = p->hy_w_out + (size_t)l * 64 * 2048 + cb * 32;
;   float acc[32];
; #pragma unroll
;   for (int cc = 0; cc < 32; ++cc) acc[cc] = 0.f;
; #pragma unroll 4
;   for (int j4 = 0; j4 < 16; ++j4) {
;     const f32x4 hv = *(const f32x4*)(hr + 4 * j4);
;     const float* w0 = wout + (size_t)(4 * j4) * 2048;
; #pragma unroll
;     for (int cc = 0; cc < 32; ++cc)
;       acc[cc] += hv.x * w0[cc] + hv.y * w0[2048 + cc] + hv.z * w0[4096 + cc] + hv.w * w0[6144 + cc];
;   }
;   const float mind = -4.605170185988091f / 1.5f, maxd = -4.605170185988091f / 0.3f;
;   const float tl = (float)t / 4095.f;
.LBB0_126:
	s_cmpk_gt_i32 s34, 0x10ff
	s_mov_b64 s[8:9], -1
	s_cbranch_scc0 .LBB0_247
	s_cmpk_gt_u32 s34, 0x1a87
	s_cbranch_scc0 .LBB0_131
	s_add_i32 s4, s34, 0xffffe578
	s_load_dwordx2 s[8:9], s[0:1], 0x130
	s_load_dwordx2 s[2:3], s[0:1], 0xd8
	s_lshl_b32 s5, s4, 2
	s_lshl_b32 s26, s4, 5
	s_and_b32 s5, s5, 0xf00
	s_and_b32 s26, s26, 0x7e0
	v_and_b32_e32 v120, 31, v0
	v_bfe_u32 v121, v0, 5, 1
	v_bfe_u32 v122, v0, 6, 2
	v_lshl_add_u32 v123, v122, 6, v120
	v_add_u32_e32 v123, s5, v123
	v_lshlrev_b32_e32 v124, 8, v123
	v_lshl_add_u32 v124, v121, 7, v124
	v_add_u32_e32 v126, 0x2000, v124
	v_lshlrev_b32_e32 v127, 2, v120
	v_lshl_add_u32 v127, v121, 18, v127
	v_readlane_b32 s18, v255, 33
	v_readlane_b32 s19, v255, 34
	s_waitcnt lgkmcnt(0)
	s_add_u32 s10, s8, s6
	s_addc_u32 s11, s9, s7
	s_add_u32 s10, s10, 0xe85c000
	s_addc_u32 s11, s11, 0
	global_load_dwordx4 v[34:37], v124, s[10:11]
	global_load_dwordx4 v[38:41], v124, s[10:11] offset:16
	global_load_dwordx4 v[42:45], v124, s[10:11] offset:32
	global_load_dwordx4 v[46:49], v124, s[10:11] offset:48
	global_load_dwordx4 v[50:53], v124, s[10:11] offset:64
	global_load_dwordx4 v[54:57], v124, s[10:11] offset:80
	global_load_dwordx4 v[58:61], v124, s[10:11] offset:96
	global_load_dwordx4 v[62:65], v124, s[10:11] offset:112
	global_load_dwordx4 v[66:69], v126, s[10:11]
	global_load_dwordx4 v[70:73], v126, s[10:11] offset:16
	global_load_dwordx4 v[74:77], v126, s[10:11] offset:32
	global_load_dwordx4 v[78:81], v126, s[10:11] offset:48
	global_load_dwordx4 v[82:85], v126, s[10:11] offset:64
	global_load_dwordx4 v[86:89], v126, s[10:11] offset:80
	global_load_dwordx4 v[90:93], v126, s[10:11] offset:96
	global_load_dwordx4 v[94:97], v126, s[10:11] offset:112
	s_add_u32 s2, s2, s18
	s_addc_u32 s3, s3, s19
	s_lshl_b32 s4, s26, 2
	s_add_u32 s2, s2, s4
	s_addc_u32 s3, s3, 0
	global_load_dword v2, v127, s[2:3]
	s_add_u32 s2, s2, 0x2000
	s_addc_u32 s3, s3, 0
	global_load_dword v3, v127, s[2:3]
	s_add_u32 s2, s2, 0x2000
	s_addc_u32 s3, s3, 0
	global_load_dword v4, v127, s[2:3]
	s_add_u32 s2, s2, 0x2000
	s_addc_u32 s3, s3, 0
	global_load_dword v5, v127, s[2:3]
	s_add_u32 s2, s2, 0x2000
	s_addc_u32 s3, s3, 0
	global_load_dword v6, v127, s[2:3]
	s_add_u32 s2, s2, 0x2000
	s_addc_u32 s3, s3, 0
	global_load_dword v7, v127, s[2:3]
	s_add_u32 s2, s2, 0x2000
	s_addc_u32 s3, s3, 0
	global_load_dword v8, v127, s[2:3]
	s_add_u32 s2, s2, 0x2000
	s_addc_u32 s3, s3, 0
	global_load_dword v9, v127, s[2:3]
	s_add_u32 s2, s2, 0x2000
	s_addc_u32 s3, s3, 0
	global_load_dword v10, v127, s[2:3]
	s_add_u32 s2, s2, 0x2000
	s_addc_u32 s3, s3, 0
	global_load_dword v11, v127, s[2:3]
	s_add_u32 s2, s2, 0x2000
	s_addc_u32 s3, s3, 0
	global_load_dword v12, v127, s[2:3]
	s_add_u32 s2, s2, 0x2000
	s_addc_u32 s3, s3, 0
	global_load_dword v13, v127, s[2:3]
	s_add_u32 s2, s2, 0x2000
	s_addc_u32 s3, s3, 0
	global_load_dword v14, v127, s[2:3]
	s_add_u32 s2, s2, 0x2000
	s_addc_u32 s3, s3, 0
	global_load_dword v15, v127, s[2:3]
	s_add_u32 s2, s2, 0x2000
	s_addc_u32 s3, s3, 0
	global_load_dword v16, v127, s[2:3]
	s_add_u32 s2, s2, 0x2000
	s_addc_u32 s3, s3, 0
	global_load_dword v17, v127, s[2:3]
	s_add_u32 s2, s2, 0x2000
	s_addc_u32 s3, s3, 0
	global_load_dword v18, v127, s[2:3]
	s_add_u32 s2, s2, 0x2000
	s_addc_u32 s3, s3, 0
	global_load_dword v19, v127, s[2:3]
	s_add_u32 s2, s2, 0x2000
	s_addc_u32 s3, s3, 0
	global_load_dword v20, v127, s[2:3]
	s_add_u32 s2, s2, 0x2000
	s_addc_u32 s3, s3, 0
	global_load_dword v21, v127, s[2:3]
	s_add_u32 s2, s2, 0x2000
	s_addc_u32 s3, s3, 0
	global_load_dword v22, v127, s[2:3]
	s_add_u32 s2, s2, 0x2000
	s_addc_u32 s3, s3, 0
	global_load_dword v23, v127, s[2:3]
	s_add_u32 s2, s2, 0x2000
	s_addc_u32 s3, s3, 0
	global_load_dword v24, v127, s[2:3]
	s_add_u32 s2, s2, 0x2000
	s_addc_u32 s3, s3, 0
	global_load_dword v25, v127, s[2:3]
	s_add_u32 s2, s2, 0x2000
	s_addc_u32 s3, s3, 0
	global_load_dword v26, v127, s[2:3]
	s_add_u32 s2, s2, 0x2000
	s_addc_u32 s3, s3, 0
	global_load_dword v27, v127, s[2:3]
	s_add_u32 s2, s2, 0x2000
	s_addc_u32 s3, s3, 0
	global_load_dword v28, v127, s[2:3]
	s_add_u32 s2, s2, 0x2000
	s_addc_u32 s3, s3, 0
	global_load_dword v29, v127, s[2:3]
	s_add_u32 s2, s2, 0x2000
	s_addc_u32 s3, s3, 0
	global_load_dword v30, v127, s[2:3]
	s_add_u32 s2, s2, 0x2000
	s_addc_u32 s3, s3, 0
	global_load_dword v31, v127, s[2:3]
	s_add_u32 s2, s2, 0x2000
	s_addc_u32 s3, s3, 0
	global_load_dword v32, v127, s[2:3]
	s_add_u32 s2, s2, 0x2000
	s_addc_u32 s3, s3, 0
	global_load_dword v33, v127, s[2:3]
	s_add_u32 s2, s2, 0x2000
	s_addc_u32 s3, s3, 0
	v_cvt_f32_i32_e32 v148, v123
	v_add_u32_e32 v152, 32, v123
	v_cvt_f32_i32_e32 v152, v152
	s_mov_b32 s4, 0xc57ff000
	s_mov_b32 s22, 0x3fb8aa3b
	s_mov_b32 s23, 0xc2ce8ed0
	s_mov_b32 s24, 0x42b17218
	v_div_scale_f32 v149, s[28:29], s4, s4, v148
	v_rcp_f32_e32 v150, v149
	s_nop 0
	v_fma_f32 v151, -v149, v150, 1.0
	v_fmac_f32_e32 v150, v151, v150
	v_div_scale_f32 v151, vcc, v148, s4, v148
	v_mul_f32_e32 v153, v151, v150
	v_fma_f32 v154, -v149, v153, v151
	v_fmac_f32_e32 v153, v154, v150
	v_fma_f32 v149, -v149, v153, v151
	v_div_fmas_f32 v149, v149, v150, v153
	v_div_fixup_f32 v163, v149, s4, v148
	v_div_scale_f32 v149, s[28:29], s4, s4, v152
	v_rcp_f32_e32 v150, v149
	s_nop 0
	v_fma_f32 v151, -v149, v150, 1.0
	v_fmac_f32_e32 v150, v151, v150
	v_div_scale_f32 v151, vcc, v152, s4, v152
	v_mul_f32_e32 v153, v151, v150
	v_fma_f32 v154, -v149, v153, v151
	v_fmac_f32_e32 v153, v154, v150
	v_fma_f32 v149, -v149, v153, v151
	v_div_fmas_f32 v149, v149, v150, v153
	v_div_fixup_f32 v164, v149, s4, v152
	v_mov_b32_e32 v160, 0xc0447cbd
	v_mov_b32_e32 v161, 0x7f800000
	s_and_b32 s35, s26, 0x1e0
	v_lshl_add_u32 v162, v121, 2, s35
	v_lshlrev_b32_e32 v165, 1, v123
	v_lshl_add_u32 v165, v121, 15, v165
	s_waitcnt vmcnt(31)
; DI void filt_unit(KP p, int l, int u) {
;     ...
; #pragma unroll 4
;   for (int j4 = 0; j4 < 16; ++j4) {
;     const f32x4 hv = *(const f32x4*)(hr + 4 * j4);
;     const float* w0 = wout + (size_t)(4 * j4) * 2048;
; #pragma unroll
;     for (int cc = 0; cc < 32; ++cc)
;       acc[cc] += hv.x * w0[cc] + hv.y * w0[2048 + cc] + hv.z * w0[4096 + cc] + hv.w * w0[6144 + cc];
;   }
;   const float mind = -4.605170185988091f / 1.5f, maxd = -4.605170185988091f / 0.3f;
;   const float tl = (float)t / 4095.f;
;   u16* F = (u16*)(p->ws + OFF_FILT);
; #pragma unroll
;   for (int cc = 0; cc < 32; ++cc) {
;     const int col = cb * 32 + cc, c = col & 511;
;     const float delta = fabsf(mind + (float)c * ((maxd - mind) / 511.f));
;     F[(size_t)col * 4096 + t] = f2bf(acc[cc] * expf(-tl * delta));
	v_mfma_f32_32x32x2_f32 v[104:119], v2, v34, 0
	v_mfma_f32_32x32x2_f32 v[132:147], v2, v66, 0
	s_waitcnt vmcnt(30)
	v_mfma_f32_32x32x2_f32 v[104:119], v3, v35, v[104:119]
	v_mfma_f32_32x32x2_f32 v[132:147], v3, v67, v[132:147]
	s_waitcnt vmcnt(29)
	v_mfma_f32_32x32x2_f32 v[104:119], v4, v36, v[104:119]
	v_mfma_f32_32x32x2_f32 v[132:147], v4, v68, v[132:147]
	s_waitcnt vmcnt(28)
	v_mfma_f32_32x32x2_f32 v[104:119], v5, v37, v[104:119]
	v_mfma_f32_32x32x2_f32 v[132:147], v5, v69, v[132:147]
	s_waitcnt vmcnt(27)
	v_mfma_f32_32x32x2_f32 v[104:119], v6, v38, v[104:119]
	v_mfma_f32_32x32x2_f32 v[132:147], v6, v70, v[132:147]
	s_waitcnt vmcnt(26)
	v_mfma_f32_32x32x2_f32 v[104:119], v7, v39, v[104:119]
	v_mfma_f32_32x32x2_f32 v[132:147], v7, v71, v[132:147]
	s_waitcnt vmcnt(25)
	v_mfma_f32_32x32x2_f32 v[104:119], v8, v40, v[104:119]
	v_mfma_f32_32x32x2_f32 v[132:147], v8, v72, v[132:147]
	s_waitcnt vmcnt(24)
	v_mfma_f32_32x32x2_f32 v[104:119], v9, v41, v[104:119]
	v_mfma_f32_32x32x2_f32 v[132:147], v9, v73, v[132:147]
	s_waitcnt vmcnt(23)
	v_mfma_f32_32x32x2_f32 v[104:119], v10, v42, v[104:119]
	v_mfma_f32_32x32x2_f32 v[132:147], v10, v74, v[132:147]
	s_waitcnt vmcnt(22)
	v_mfma_f32_32x32x2_f32 v[104:119], v11, v43, v[104:119]
	v_mfma_f32_32x32x2_f32 v[132:147], v11, v75, v[132:147]
	s_waitcnt vmcnt(21)
	v_mfma_f32_32x32x2_f32 v[104:119], v12, v44, v[104:119]
	v_mfma_f32_32x32x2_f32 v[132:147], v12, v76, v[132:147]
	s_waitcnt vmcnt(20)
	v_mfma_f32_32x32x2_f32 v[104:119], v13, v45, v[104:119]
	v_mfma_f32_32x32x2_f32 v[132:147], v13, v77, v[132:147]
	s_waitcnt vmcnt(19)
	v_mfma_f32_32x32x2_f32 v[104:119], v14, v46, v[104:119]
	v_mfma_f32_32x32x2_f32 v[132:147], v14, v78, v[132:147]
	s_waitcnt vmcnt(18)
	v_mfma_f32_32x32x2_f32 v[104:119], v15, v47, v[104:119]
	v_mfma_f32_32x32x2_f32 v[132:147], v15, v79, v[132:147]
	s_waitcnt vmcnt(17)
	v_mfma_f32_32x32x2_f32 v[104:119], v16, v48, v[104:119]
	v_mfma_f32_32x32x2_f32 v[132:147], v16, v80, v[132:147]
	s_waitcnt vmcnt(16)
	v_mfma_f32_32x32x2_f32 v[104:119], v17, v49, v[104:119]
	v_mfma_f32_32x32x2_f32 v[132:147], v17, v81, v[132:147]
	s_waitcnt vmcnt(15)
	v_mfma_f32_32x32x2_f32 v[104:119], v18, v50, v[104:119]
	v_mfma_f32_32x32x2_f32 v[132:147], v18, v82, v[132:147]
	s_waitcnt vmcnt(14)
	v_mfma_f32_32x32x2_f32 v[104:119], v19, v51, v[104:119]
	v_mfma_f32_32x32x2_f32 v[132:147], v19, v83, v[132:147]
	s_waitcnt vmcnt(13)
	v_mfma_f32_32x32x2_f32 v[104:119], v20, v52, v[104:119]
	v_mfma_f32_32x32x2_f32 v[132:147], v20, v84, v[132:147]
	s_waitcnt vmcnt(12)
	v_mfma_f32_32x32x2_f32 v[104:119], v21, v53, v[104:119]
	v_mfma_f32_32x32x2_f32 v[132:147], v21, v85, v[132:147]
	s_waitcnt vmcnt(11)
	v_mfma_f32_32x32x2_f32 v[104:119], v22, v54, v[104:119]
	v_mfma_f32_32x32x2_f32 v[132:147], v22, v86, v[132:147]
	s_waitcnt vmcnt(10)
	v_mfma_f32_32x32x2_f32 v[104:119], v23, v55, v[104:119]
	v_mfma_f32_32x32x2_f32 v[132:147], v23, v87, v[132:147]
	s_waitcnt vmcnt(9)
	v_mfma_f32_32x32x2_f32 v[104:119], v24, v56, v[104:119]
	v_mfma_f32_32x32x2_f32 v[132:147], v24, v88, v[132:147]
	s_waitcnt vmcnt(8)
	v_mfma_f32_32x32x2_f32 v[104:119], v25, v57, v[104:119]
	v_mfma_f32_32x32x2_f32 v[132:147], v25, v89, v[132:147]
	s_waitcnt vmcnt(7)
	v_mfma_f32_32x32x2_f32 v[104:119], v26, v58, v[104:119]
	v_mfma_f32_32x32x2_f32 v[132:147], v26, v90, v[132:147]
	s_waitcnt vmcnt(6)
	v_mfma_f32_32x32x2_f32 v[104:119], v27, v59, v[104:119]
	v_mfma_f32_32x32x2_f32 v[132:147], v27, v91, v[132:147]
	s_waitcnt vmcnt(5)
	v_mfma_f32_32x32x2_f32 v[104:119], v28, v60, v[104:119]
	v_mfma_f32_32x32x2_f32 v[132:147], v28, v92, v[132:147]
	s_waitcnt vmcnt(4)
	v_mfma_f32_32x32x2_f32 v[104:119], v29, v61, v[104:119]
	v_mfma_f32_32x32x2_f32 v[132:147], v29, v93, v[132:147]
	s_waitcnt vmcnt(3)
	v_mfma_f32_32x32x2_f32 v[104:119], v30, v62, v[104:119]
	v_mfma_f32_32x32x2_f32 v[132:147], v30, v94, v[132:147]
	s_waitcnt vmcnt(2)
	v_mfma_f32_32x32x2_f32 v[104:119], v31, v63, v[104:119]
	v_mfma_f32_32x32x2_f32 v[132:147], v31, v95, v[132:147]
	s_waitcnt vmcnt(1)
	v_mfma_f32_32x32x2_f32 v[104:119], v32, v64, v[104:119]
	v_mfma_f32_32x32x2_f32 v[132:147], v32, v96, v[132:147]
	s_waitcnt vmcnt(0)
	v_mfma_f32_32x32x2_f32 v[104:119], v33, v65, v[104:119]
	v_mfma_f32_32x32x2_f32 v[132:147], v33, v97, v[132:147]
	s_lshl_b32 s4, s26, 13
	s_add_u32 s2, s8, s4
	s_addc_u32 s3, s9, 0
	s_add_u32 s2, s2, 0xec9c000
	s_addc_u32 s3, s3, 0
	s_nop 15
	s_nop 7
	v_add_u32_e32 v157, 0, v162
	v_mov_b32_e32 v158, v165
	v_cvt_f32_u32_e32 v157, v157
	v_fmamk_f32 v156, v157, 0xbcc4df2d, v160
	v_mul_f32_e64 v148, |v156|, v163
	v_mul_f32_e64 v152, |v156|, v164
	v_mul_f32_e32 v149, 0x3fb8aa3b, v148
	v_mul_f32_e32 v153, 0x3fb8aa3b, v152
	v_fma_f32 v150, v148, s22, -v149
	v_fma_f32 v154, v152, s22, -v153
	v_rndne_f32_e32 v151, v149
	v_rndne_f32_e32 v155, v153
	v_fmac_f32_e32 v150, 0x32a5705f, v148
	v_fmac_f32_e32 v154, 0x32a5705f, v152
	v_sub_f32_e32 v149, v149, v151
	v_sub_f32_e32 v153, v153, v155
	v_add_f32_e32 v149, v149, v150
	v_add_f32_e32 v153, v153, v154
	v_exp_f32_e32 v149, v149
	v_exp_f32_e32 v153, v153
	v_cvt_i32_f32_e32 v150, v151
	v_cvt_i32_f32_e32 v154, v155
	v_cmp_ngt_f32_e64 s[10:11], s23, v148
	v_cmp_ngt_f32_e64 s[18:19], s23, v152
	v_ldexp_f32 v149, v149, v150
	v_ldexp_f32 v153, v153, v154
	v_cndmask_b32_e64 v149, 0, v149, s[10:11]
	v_cndmask_b32_e64 v153, 0, v153, s[18:19]
	v_cmp_nlt_f32_e64 s[10:11], s24, v148
	v_cmp_nlt_f32_e64 s[18:19], s24, v152
	s_nop 1
	v_cndmask_b32_e64 v148, v161, v149, s[10:11]
	v_cndmask_b32_e64 v152, v161, v153, s[18:19]
	v_mul_f32_e32 v148, v148, v104
	v_mul_f32_e32 v152, v152, v132
	v_cvt_pk_bf16_f32 v148, v148, v148
	v_cvt_pk_bf16_f32 v152, v152, v152
; DI void filt_unit(KP p, int l, int u) {
;     ...
; #pragma unroll
;   for (int cc = 0; cc < 32; ++cc) {
;     const int col = cb * 32 + cc, c = col & 511;
;     const float delta = fabsf(mind + (float)c * ((maxd - mind) / 511.f));
;     F[(size_t)col * 4096 + t] = f2bf(acc[cc] * expf(-tl * delta));
;   }
	global_store_short v158, v148, s[2:3]
	global_store_short v158, v152, s[2:3] offset:64
	v_add_u32_e32 v157, 1, v162
	v_add_u32_e32 v158, 0x2000, v165
	v_cvt_f32_u32_e32 v157, v157
	v_fmamk_f32 v156, v157, 0xbcc4df2d, v160
	v_mul_f32_e64 v148, |v156|, v163
	v_mul_f32_e64 v152, |v156|, v164
	v_mul_f32_e32 v149, 0x3fb8aa3b, v148
	v_mul_f32_e32 v153, 0x3fb8aa3b, v152
	v_fma_f32 v150, v148, s22, -v149
	v_fma_f32 v154, v152, s22, -v153
	v_rndne_f32_e32 v151, v149
	v_rndne_f32_e32 v155, v153
	v_fmac_f32_e32 v150, 0x32a5705f, v148
	v_fmac_f32_e32 v154, 0x32a5705f, v152
	v_sub_f32_e32 v149, v149, v151
	v_sub_f32_e32 v153, v153, v155
	v_add_f32_e32 v149, v149, v150
	v_add_f32_e32 v153, v153, v154
	v_exp_f32_e32 v149, v149
	v_exp_f32_e32 v153, v153
	v_cvt_i32_f32_e32 v150, v151
	v_cvt_i32_f32_e32 v154, v155
	v_cmp_ngt_f32_e64 s[10:11], s23, v148
	v_cmp_ngt_f32_e64 s[18:19], s23, v152
	v_ldexp_f32 v149, v149, v150
	v_ldexp_f32 v153, v153, v154
	v_cndmask_b32_e64 v149, 0, v149, s[10:11]
	v_cndmask_b32_e64 v153, 0, v153, s[18:19]
	v_cmp_nlt_f32_e64 s[10:11], s24, v148
	v_cmp_nlt_f32_e64 s[18:19], s24, v152
	s_nop 1
	v_cndmask_b32_e64 v148, v161, v149, s[10:11]
	v_cndmask_b32_e64 v152, v161, v153, s[18:19]
	v_mul_f32_e32 v148, v148, v105
	v_mul_f32_e32 v152, v152, v133
	v_cvt_pk_bf16_f32 v148, v148, v148
	v_cvt_pk_bf16_f32 v152, v152, v152
	global_store_short v158, v148, s[2:3]
	global_store_short v158, v152, s[2:3] offset:64
	v_add_u32_e32 v157, 2, v162
	v_add_u32_e32 v158, 0x4000, v165
	v_cvt_f32_u32_e32 v157, v157
	v_fmamk_f32 v156, v157, 0xbcc4df2d, v160
	v_mul_f32_e64 v148, |v156|, v163
	v_mul_f32_e64 v152, |v156|, v164
	v_mul_f32_e32 v149, 0x3fb8aa3b, v148
	v_mul_f32_e32 v153, 0x3fb8aa3b, v152
	v_fma_f32 v150, v148, s22, -v149
	v_fma_f32 v154, v152, s22, -v153
	v_rndne_f32_e32 v151, v149
	v_rndne_f32_e32 v155, v153
	v_fmac_f32_e32 v150, 0x32a5705f, v148
	v_fmac_f32_e32 v154, 0x32a5705f, v152
	v_sub_f32_e32 v149, v149, v151
	v_sub_f32_e32 v153, v153, v155
	v_add_f32_e32 v149, v149, v150
	v_add_f32_e32 v153, v153, v154
	v_exp_f32_e32 v149, v149
	v_exp_f32_e32 v153, v153
	v_cvt_i32_f32_e32 v150, v151
	v_cvt_i32_f32_e32 v154, v155
	v_cmp_ngt_f32_e64 s[10:11], s23, v148
	v_cmp_ngt_f32_e64 s[18:19], s23, v152
	v_ldexp_f32 v149, v149, v150
	v_ldexp_f32 v153, v153, v154
	v_cndmask_b32_e64 v149, 0, v149, s[10:11]
	v_cndmask_b32_e64 v153, 0, v153, s[18:19]
	v_cmp_nlt_f32_e64 s[10:11], s24, v148
	v_cmp_nlt_f32_e64 s[18:19], s24, v152
	s_nop 1
	v_cndmask_b32_e64 v148, v161, v149, s[10:11]
	v_cndmask_b32_e64 v152, v161, v153, s[18:19]
	v_mul_f32_e32 v148, v148, v106
	v_mul_f32_e32 v152, v152, v134
	v_cvt_pk_bf16_f32 v148, v148, v148
	v_cvt_pk_bf16_f32 v152, v152, v152
	global_store_short v158, v148, s[2:3]
	global_store_short v158, v152, s[2:3] offset:64
	v_add_u32_e32 v157, 3, v162
	v_add_u32_e32 v158, 0x6000, v165
	v_cvt_f32_u32_e32 v157, v157
	v_fmamk_f32 v156, v157, 0xbcc4df2d, v160
	v_mul_f32_e64 v148, |v156|, v163
	v_mul_f32_e64 v152, |v156|, v164
	v_mul_f32_e32 v149, 0x3fb8aa3b, v148
	v_mul_f32_e32 v153, 0x3fb8aa3b, v152
	v_fma_f32 v150, v148, s22, -v149
	v_fma_f32 v154, v152, s22, -v153
	v_rndne_f32_e32 v151, v149
	v_rndne_f32_e32 v155, v153
	v_fmac_f32_e32 v150, 0x32a5705f, v148
	v_fmac_f32_e32 v154, 0x32a5705f, v152
	v_sub_f32_e32 v149, v149, v151
	v_sub_f32_e32 v153, v153, v155
	v_add_f32_e32 v149, v149, v150
	v_add_f32_e32 v153, v153, v154
	v_exp_f32_e32 v149, v149
	v_exp_f32_e32 v153, v153
	v_cvt_i32_f32_e32 v150, v151
	v_cvt_i32_f32_e32 v154, v155
	v_cmp_ngt_f32_e64 s[10:11], s23, v148
	v_cmp_ngt_f32_e64 s[18:19], s23, v152
	v_ldexp_f32 v149, v149, v150
	v_ldexp_f32 v153, v153, v154
	v_cndmask_b32_e64 v149, 0, v149, s[10:11]
	v_cndmask_b32_e64 v153, 0, v153, s[18:19]
	v_cmp_nlt_f32_e64 s[10:11], s24, v148
	v_cmp_nlt_f32_e64 s[18:19], s24, v152
	s_nop 1
	v_cndmask_b32_e64 v148, v161, v149, s[10:11]
	v_cndmask_b32_e64 v152, v161, v153, s[18:19]
	v_mul_f32_e32 v148, v148, v107
	v_mul_f32_e32 v152, v152, v135
	v_cvt_pk_bf16_f32 v148, v148, v148
	v_cvt_pk_bf16_f32 v152, v152, v152
	global_store_short v158, v148, s[2:3]
	global_store_short v158, v152, s[2:3] offset:64
	v_add_u32_e32 v157, 8, v162
	v_add_u32_e32 v158, 0x10000, v165
	v_cvt_f32_u32_e32 v157, v157
	v_fmamk_f32 v156, v157, 0xbcc4df2d, v160
	v_mul_f32_e64 v148, |v156|, v163
	v_mul_f32_e64 v152, |v156|, v164
	v_mul_f32_e32 v149, 0x3fb8aa3b, v148
	v_mul_f32_e32 v153, 0x3fb8aa3b, v152
	v_fma_f32 v150, v148, s22, -v149
	v_fma_f32 v154, v152, s22, -v153
	v_rndne_f32_e32 v151, v149
	v_rndne_f32_e32 v155, v153
	v_fmac_f32_e32 v150, 0x32a5705f, v148
	v_fmac_f32_e32 v154, 0x32a5705f, v152
	v_sub_f32_e32 v149, v149, v151
	v_sub_f32_e32 v153, v153, v155
	v_add_f32_e32 v149, v149, v150
	v_add_f32_e32 v153, v153, v154
	v_exp_f32_e32 v149, v149
	v_exp_f32_e32 v153, v153
	v_cvt_i32_f32_e32 v150, v151
	v_cvt_i32_f32_e32 v154, v155
	v_cmp_ngt_f32_e64 s[10:11], s23, v148
	v_cmp_ngt_f32_e64 s[18:19], s23, v152
	v_ldexp_f32 v149, v149, v150
	v_ldexp_f32 v153, v153, v154
	v_cndmask_b32_e64 v149, 0, v149, s[10:11]
	v_cndmask_b32_e64 v153, 0, v153, s[18:19]
	v_cmp_nlt_f32_e64 s[10:11], s24, v148
	v_cmp_nlt_f32_e64 s[18:19], s24, v152
	s_nop 1
	v_cndmask_b32_e64 v148, v161, v149, s[10:11]
	v_cndmask_b32_e64 v152, v161, v153, s[18:19]
	v_mul_f32_e32 v148, v148, v108
	v_mul_f32_e32 v152, v152, v136
	v_cvt_pk_bf16_f32 v148, v148, v148
	v_cvt_pk_bf16_f32 v152, v152, v152
	global_store_short v158, v148, s[2:3]
	global_store_short v158, v152, s[2:3] offset:64
	v_add_u32_e32 v157, 9, v162
	v_add_u32_e32 v158, 0x12000, v165
	v_cvt_f32_u32_e32 v157, v157
	v_fmamk_f32 v156, v157, 0xbcc4df2d, v160
	v_mul_f32_e64 v148, |v156|, v163
; DI void filt_unit(KP p, int l, int u) {
;     ...
; #pragma unroll
;   for (int cc = 0; cc < 32; ++cc) {
;     const int col = cb * 32 + cc, c = col & 511;
;     const float delta = fabsf(mind + (float)c * ((maxd - mind) / 511.f));
;     F[(size_t)col * 4096 + t] = f2bf(acc[cc] * expf(-tl * delta));
;   }
	v_mul_f32_e64 v152, |v156|, v164
	v_mul_f32_e32 v149, 0x3fb8aa3b, v148
	v_mul_f32_e32 v153, 0x3fb8aa3b, v152
	v_fma_f32 v150, v148, s22, -v149
	v_fma_f32 v154, v152, s22, -v153
	v_rndne_f32_e32 v151, v149
	v_rndne_f32_e32 v155, v153
	v_fmac_f32_e32 v150, 0x32a5705f, v148
	v_fmac_f32_e32 v154, 0x32a5705f, v152
	v_sub_f32_e32 v149, v149, v151
	v_sub_f32_e32 v153, v153, v155
	v_add_f32_e32 v149, v149, v150
	v_add_f32_e32 v153, v153, v154
	v_exp_f32_e32 v149, v149
	v_exp_f32_e32 v153, v153
	v_cvt_i32_f32_e32 v150, v151
	v_cvt_i32_f32_e32 v154, v155
	v_cmp_ngt_f32_e64 s[10:11], s23, v148
	v_cmp_ngt_f32_e64 s[18:19], s23, v152
	v_ldexp_f32 v149, v149, v150
	v_ldexp_f32 v153, v153, v154
	v_cndmask_b32_e64 v149, 0, v149, s[10:11]
	v_cndmask_b32_e64 v153, 0, v153, s[18:19]
	v_cmp_nlt_f32_e64 s[10:11], s24, v148
	v_cmp_nlt_f32_e64 s[18:19], s24, v152
	s_nop 1
	v_cndmask_b32_e64 v148, v161, v149, s[10:11]
	v_cndmask_b32_e64 v152, v161, v153, s[18:19]
	v_mul_f32_e32 v148, v148, v109
	v_mul_f32_e32 v152, v152, v137
	v_cvt_pk_bf16_f32 v148, v148, v148
	v_cvt_pk_bf16_f32 v152, v152, v152
	global_store_short v158, v148, s[2:3]
	global_store_short v158, v152, s[2:3] offset:64
	v_add_u32_e32 v157, 10, v162
	v_add_u32_e32 v158, 0x14000, v165
	v_cvt_f32_u32_e32 v157, v157
	v_fmamk_f32 v156, v157, 0xbcc4df2d, v160
	v_mul_f32_e64 v148, |v156|, v163
	v_mul_f32_e64 v152, |v156|, v164
	v_mul_f32_e32 v149, 0x3fb8aa3b, v148
	v_mul_f32_e32 v153, 0x3fb8aa3b, v152
	v_fma_f32 v150, v148, s22, -v149
	v_fma_f32 v154, v152, s22, -v153
	v_rndne_f32_e32 v151, v149
	v_rndne_f32_e32 v155, v153
	v_fmac_f32_e32 v150, 0x32a5705f, v148
	v_fmac_f32_e32 v154, 0x32a5705f, v152
	v_sub_f32_e32 v149, v149, v151
	v_sub_f32_e32 v153, v153, v155
	v_add_f32_e32 v149, v149, v150
	v_add_f32_e32 v153, v153, v154
	v_exp_f32_e32 v149, v149
	v_exp_f32_e32 v153, v153
	v_cvt_i32_f32_e32 v150, v151
	v_cvt_i32_f32_e32 v154, v155
	v_cmp_ngt_f32_e64 s[10:11], s23, v148
	v_cmp_ngt_f32_e64 s[18:19], s23, v152
	v_ldexp_f32 v149, v149, v150
	v_ldexp_f32 v153, v153, v154
	v_cndmask_b32_e64 v149, 0, v149, s[10:11]
	v_cndmask_b32_e64 v153, 0, v153, s[18:19]
	v_cmp_nlt_f32_e64 s[10:11], s24, v148
	v_cmp_nlt_f32_e64 s[18:19], s24, v152
	s_nop 1
	v_cndmask_b32_e64 v148, v161, v149, s[10:11]
	v_cndmask_b32_e64 v152, v161, v153, s[18:19]
	v_mul_f32_e32 v148, v148, v110
	v_mul_f32_e32 v152, v152, v138
	v_cvt_pk_bf16_f32 v148, v148, v148
	v_cvt_pk_bf16_f32 v152, v152, v152
	global_store_short v158, v148, s[2:3]
	global_store_short v158, v152, s[2:3] offset:64
	v_add_u32_e32 v157, 11, v162
	v_add_u32_e32 v158, 0x16000, v165
	v_cvt_f32_u32_e32 v157, v157
	v_fmamk_f32 v156, v157, 0xbcc4df2d, v160
	v_mul_f32_e64 v148, |v156|, v163
	v_mul_f32_e64 v152, |v156|, v164
	v_mul_f32_e32 v149, 0x3fb8aa3b, v148
	v_mul_f32_e32 v153, 0x3fb8aa3b, v152
	v_fma_f32 v150, v148, s22, -v149
	v_fma_f32 v154, v152, s22, -v153
	v_rndne_f32_e32 v151, v149
	v_rndne_f32_e32 v155, v153
	v_fmac_f32_e32 v150, 0x32a5705f, v148
	v_fmac_f32_e32 v154, 0x32a5705f, v152
	v_sub_f32_e32 v149, v149, v151
	v_sub_f32_e32 v153, v153, v155
	v_add_f32_e32 v149, v149, v150
	v_add_f32_e32 v153, v153, v154
	v_exp_f32_e32 v149, v149
	v_exp_f32_e32 v153, v153
	v_cvt_i32_f32_e32 v150, v151
	v_cvt_i32_f32_e32 v154, v155
	v_cmp_ngt_f32_e64 s[10:11], s23, v148
	v_cmp_ngt_f32_e64 s[18:19], s23, v152
	v_ldexp_f32 v149, v149, v150
	v_ldexp_f32 v153, v153, v154
	v_cndmask_b32_e64 v149, 0, v149, s[10:11]
	v_cndmask_b32_e64 v153, 0, v153, s[18:19]
	v_cmp_nlt_f32_e64 s[10:11], s24, v148
	v_cmp_nlt_f32_e64 s[18:19], s24, v152
	s_nop 1
	v_cndmask_b32_e64 v148, v161, v149, s[10:11]
	v_cndmask_b32_e64 v152, v161, v153, s[18:19]
	v_mul_f32_e32 v148, v148, v111
	v_mul_f32_e32 v152, v152, v139
	v_cvt_pk_bf16_f32 v148, v148, v148
	v_cvt_pk_bf16_f32 v152, v152, v152
	global_store_short v158, v148, s[2:3]
	global_store_short v158, v152, s[2:3] offset:64
	v_add_u32_e32 v157, 16, v162
	v_add_u32_e32 v158, 0x20000, v165
	v_cvt_f32_u32_e32 v157, v157
	v_fmamk_f32 v156, v157, 0xbcc4df2d, v160
	v_mul_f32_e64 v148, |v156|, v163
	v_mul_f32_e64 v152, |v156|, v164
	v_mul_f32_e32 v149, 0x3fb8aa3b, v148
	v_mul_f32_e32 v153, 0x3fb8aa3b, v152
	v_fma_f32 v150, v148, s22, -v149
	v_fma_f32 v154, v152, s22, -v153
	v_rndne_f32_e32 v151, v149
	v_rndne_f32_e32 v155, v153
	v_fmac_f32_e32 v150, 0x32a5705f, v148
	v_fmac_f32_e32 v154, 0x32a5705f, v152
	v_sub_f32_e32 v149, v149, v151
	v_sub_f32_e32 v153, v153, v155
	v_add_f32_e32 v149, v149, v150
	v_add_f32_e32 v153, v153, v154
	v_exp_f32_e32 v149, v149
	v_exp_f32_e32 v153, v153
	v_cvt_i32_f32_e32 v150, v151
	v_cvt_i32_f32_e32 v154, v155
	v_cmp_ngt_f32_e64 s[10:11], s23, v148
	v_cmp_ngt_f32_e64 s[18:19], s23, v152
	v_ldexp_f32 v149, v149, v150
	v_ldexp_f32 v153, v153, v154
	v_cndmask_b32_e64 v149, 0, v149, s[10:11]
	v_cndmask_b32_e64 v153, 0, v153, s[18:19]
	v_cmp_nlt_f32_e64 s[10:11], s24, v148
	v_cmp_nlt_f32_e64 s[18:19], s24, v152
	s_nop 1
	v_cndmask_b32_e64 v148, v161, v149, s[10:11]
	v_cndmask_b32_e64 v152, v161, v153, s[18:19]
	v_mul_f32_e32 v148, v148, v112
	v_mul_f32_e32 v152, v152, v140
	v_cvt_pk_bf16_f32 v148, v148, v148
	v_cvt_pk_bf16_f32 v152, v152, v152
	global_store_short v158, v148, s[2:3]
	global_store_short v158, v152, s[2:3] offset:64
	v_add_u32_e32 v157, 17, v162
	v_add_u32_e32 v158, 0x22000, v165
	v_cvt_f32_u32_e32 v157, v157
	v_fmamk_f32 v156, v157, 0xbcc4df2d, v160
	v_mul_f32_e64 v148, |v156|, v163
	v_mul_f32_e64 v152, |v156|, v164
	v_mul_f32_e32 v149, 0x3fb8aa3b, v148
	v_mul_f32_e32 v153, 0x3fb8aa3b, v152
	v_fma_f32 v150, v148, s22, -v149
	v_fma_f32 v154, v152, s22, -v153
	v_rndne_f32_e32 v151, v149
	v_rndne_f32_e32 v155, v153
; DI void filt_unit(KP p, int l, int u) {
;     ...
; #pragma unroll
;   for (int cc = 0; cc < 32; ++cc) {
;     const int col = cb * 32 + cc, c = col & 511;
;     const float delta = fabsf(mind + (float)c * ((maxd - mind) / 511.f));
;     F[(size_t)col * 4096 + t] = f2bf(acc[cc] * expf(-tl * delta));
;   }
	v_fmac_f32_e32 v150, 0x32a5705f, v148
	v_fmac_f32_e32 v154, 0x32a5705f, v152
	v_sub_f32_e32 v149, v149, v151
	v_sub_f32_e32 v153, v153, v155
	v_add_f32_e32 v149, v149, v150
	v_add_f32_e32 v153, v153, v154
	v_exp_f32_e32 v149, v149
	v_exp_f32_e32 v153, v153
	v_cvt_i32_f32_e32 v150, v151
	v_cvt_i32_f32_e32 v154, v155
	v_cmp_ngt_f32_e64 s[10:11], s23, v148
	v_cmp_ngt_f32_e64 s[18:19], s23, v152
	v_ldexp_f32 v149, v149, v150
	v_ldexp_f32 v153, v153, v154
	v_cndmask_b32_e64 v149, 0, v149, s[10:11]
	v_cndmask_b32_e64 v153, 0, v153, s[18:19]
	v_cmp_nlt_f32_e64 s[10:11], s24, v148
	v_cmp_nlt_f32_e64 s[18:19], s24, v152
	s_nop 1
	v_cndmask_b32_e64 v148, v161, v149, s[10:11]
	v_cndmask_b32_e64 v152, v161, v153, s[18:19]
	v_mul_f32_e32 v148, v148, v113
	v_mul_f32_e32 v152, v152, v141
	v_cvt_pk_bf16_f32 v148, v148, v148
	v_cvt_pk_bf16_f32 v152, v152, v152
	global_store_short v158, v148, s[2:3]
	global_store_short v158, v152, s[2:3] offset:64
	v_add_u32_e32 v157, 18, v162
	v_add_u32_e32 v158, 0x24000, v165
	v_cvt_f32_u32_e32 v157, v157
	v_fmamk_f32 v156, v157, 0xbcc4df2d, v160
	v_mul_f32_e64 v148, |v156|, v163
	v_mul_f32_e64 v152, |v156|, v164
	v_mul_f32_e32 v149, 0x3fb8aa3b, v148
	v_mul_f32_e32 v153, 0x3fb8aa3b, v152
	v_fma_f32 v150, v148, s22, -v149
	v_fma_f32 v154, v152, s22, -v153
	v_rndne_f32_e32 v151, v149
	v_rndne_f32_e32 v155, v153
	v_fmac_f32_e32 v150, 0x32a5705f, v148
	v_fmac_f32_e32 v154, 0x32a5705f, v152
	v_sub_f32_e32 v149, v149, v151
	v_sub_f32_e32 v153, v153, v155
	v_add_f32_e32 v149, v149, v150
	v_add_f32_e32 v153, v153, v154
	v_exp_f32_e32 v149, v149
	v_exp_f32_e32 v153, v153
	v_cvt_i32_f32_e32 v150, v151
	v_cvt_i32_f32_e32 v154, v155
	v_cmp_ngt_f32_e64 s[10:11], s23, v148
	v_cmp_ngt_f32_e64 s[18:19], s23, v152
	v_ldexp_f32 v149, v149, v150
	v_ldexp_f32 v153, v153, v154
	v_cndmask_b32_e64 v149, 0, v149, s[10:11]
	v_cndmask_b32_e64 v153, 0, v153, s[18:19]
	v_cmp_nlt_f32_e64 s[10:11], s24, v148
	v_cmp_nlt_f32_e64 s[18:19], s24, v152
	s_nop 1
	v_cndmask_b32_e64 v148, v161, v149, s[10:11]
	v_cndmask_b32_e64 v152, v161, v153, s[18:19]
	v_mul_f32_e32 v148, v148, v114
	v_mul_f32_e32 v152, v152, v142
	v_cvt_pk_bf16_f32 v148, v148, v148
	v_cvt_pk_bf16_f32 v152, v152, v152
	global_store_short v158, v148, s[2:3]
	global_store_short v158, v152, s[2:3] offset:64
	v_add_u32_e32 v157, 19, v162
	v_add_u32_e32 v158, 0x26000, v165
	v_cvt_f32_u32_e32 v157, v157
	v_fmamk_f32 v156, v157, 0xbcc4df2d, v160
	v_mul_f32_e64 v148, |v156|, v163
	v_mul_f32_e64 v152, |v156|, v164
	v_mul_f32_e32 v149, 0x3fb8aa3b, v148
	v_mul_f32_e32 v153, 0x3fb8aa3b, v152
	v_fma_f32 v150, v148, s22, -v149
	v_fma_f32 v154, v152, s22, -v153
	v_rndne_f32_e32 v151, v149
	v_rndne_f32_e32 v155, v153
	v_fmac_f32_e32 v150, 0x32a5705f, v148
	v_fmac_f32_e32 v154, 0x32a5705f, v152
	v_sub_f32_e32 v149, v149, v151
	v_sub_f32_e32 v153, v153, v155
	v_add_f32_e32 v149, v149, v150
	v_add_f32_e32 v153, v153, v154
	v_exp_f32_e32 v149, v149
	v_exp_f32_e32 v153, v153
	v_cvt_i32_f32_e32 v150, v151
	v_cvt_i32_f32_e32 v154, v155
	v_cmp_ngt_f32_e64 s[10:11], s23, v148
	v_cmp_ngt_f32_e64 s[18:19], s23, v152
	v_ldexp_f32 v149, v149, v150
	v_ldexp_f32 v153, v153, v154
	v_cndmask_b32_e64 v149, 0, v149, s[10:11]
	v_cndmask_b32_e64 v153, 0, v153, s[18:19]
	v_cmp_nlt_f32_e64 s[10:11], s24, v148
	v_cmp_nlt_f32_e64 s[18:19], s24, v152
	s_nop 1
	v_cndmask_b32_e64 v148, v161, v149, s[10:11]
	v_cndmask_b32_e64 v152, v161, v153, s[18:19]
	v_mul_f32_e32 v148, v148, v115
	v_mul_f32_e32 v152, v152, v143
	v_cvt_pk_bf16_f32 v148, v148, v148
	v_cvt_pk_bf16_f32 v152, v152, v152
	global_store_short v158, v148, s[2:3]
	global_store_short v158, v152, s[2:3] offset:64
	v_add_u32_e32 v157, 24, v162
	v_add_u32_e32 v158, 0x30000, v165
	v_cvt_f32_u32_e32 v157, v157
	v_fmamk_f32 v156, v157, 0xbcc4df2d, v160
	v_mul_f32_e64 v148, |v156|, v163
	v_mul_f32_e64 v152, |v156|, v164
	v_mul_f32_e32 v149, 0x3fb8aa3b, v148
	v_mul_f32_e32 v153, 0x3fb8aa3b, v152
	v_fma_f32 v150, v148, s22, -v149
	v_fma_f32 v154, v152, s22, -v153
	v_rndne_f32_e32 v151, v149
	v_rndne_f32_e32 v155, v153
	v_fmac_f32_e32 v150, 0x32a5705f, v148
	v_fmac_f32_e32 v154, 0x32a5705f, v152
	v_sub_f32_e32 v149, v149, v151
	v_sub_f32_e32 v153, v153, v155
	v_add_f32_e32 v149, v149, v150
	v_add_f32_e32 v153, v153, v154
	v_exp_f32_e32 v149, v149
	v_exp_f32_e32 v153, v153
	v_cvt_i32_f32_e32 v150, v151
	v_cvt_i32_f32_e32 v154, v155
	v_cmp_ngt_f32_e64 s[10:11], s23, v148
	v_cmp_ngt_f32_e64 s[18:19], s23, v152
	v_ldexp_f32 v149, v149, v150
	v_ldexp_f32 v153, v153, v154
	v_cndmask_b32_e64 v149, 0, v149, s[10:11]
; DI void filt_unit(KP p, int l, int u) {
;     ...
; #pragma unroll
;   for (int cc = 0; cc < 32; ++cc) {
;     const int col = cb * 32 + cc, c = col & 511;
;     const float delta = fabsf(mind + (float)c * ((maxd - mind) / 511.f));
;     F[(size_t)col * 4096 + t] = f2bf(acc[cc] * expf(-tl * delta));
;   }
	v_cndmask_b32_e64 v153, 0, v153, s[18:19]
	v_cmp_nlt_f32_e64 s[10:11], s24, v148
	v_cmp_nlt_f32_e64 s[18:19], s24, v152
	s_nop 1
	v_cndmask_b32_e64 v148, v161, v149, s[10:11]
	v_cndmask_b32_e64 v152, v161, v153, s[18:19]
	v_mul_f32_e32 v148, v148, v116
	v_mul_f32_e32 v152, v152, v144
	v_cvt_pk_bf16_f32 v148, v148, v148
	v_cvt_pk_bf16_f32 v152, v152, v152
	global_store_short v158, v148, s[2:3]
	global_store_short v158, v152, s[2:3] offset:64
	v_add_u32_e32 v157, 25, v162
	v_add_u32_e32 v158, 0x32000, v165
	v_cvt_f32_u32_e32 v157, v157
	v_fmamk_f32 v156, v157, 0xbcc4df2d, v160
	v_mul_f32_e64 v148, |v156|, v163
	v_mul_f32_e64 v152, |v156|, v164
	v_mul_f32_e32 v149, 0x3fb8aa3b, v148
	v_mul_f32_e32 v153, 0x3fb8aa3b, v152
	v_fma_f32 v150, v148, s22, -v149
	v_fma_f32 v154, v152, s22, -v153
	v_rndne_f32_e32 v151, v149
	v_rndne_f32_e32 v155, v153
	v_fmac_f32_e32 v150, 0x32a5705f, v148
	v_fmac_f32_e32 v154, 0x32a5705f, v152
	v_sub_f32_e32 v149, v149, v151
	v_sub_f32_e32 v153, v153, v155
	v_add_f32_e32 v149, v149, v150
	v_add_f32_e32 v153, v153, v154
	v_exp_f32_e32 v149, v149
	v_exp_f32_e32 v153, v153
	v_cvt_i32_f32_e32 v150, v151
	v_cvt_i32_f32_e32 v154, v155
	v_cmp_ngt_f32_e64 s[10:11], s23, v148
	v_cmp_ngt_f32_e64 s[18:19], s23, v152
	v_ldexp_f32 v149, v149, v150
	v_ldexp_f32 v153, v153, v154
	v_cndmask_b32_e64 v149, 0, v149, s[10:11]
	v_cndmask_b32_e64 v153, 0, v153, s[18:19]
	v_cmp_nlt_f32_e64 s[10:11], s24, v148
	v_cmp_nlt_f32_e64 s[18:19], s24, v152
	s_nop 1
	v_cndmask_b32_e64 v148, v161, v149, s[10:11]
	v_cndmask_b32_e64 v152, v161, v153, s[18:19]
	v_mul_f32_e32 v148, v148, v117
	v_mul_f32_e32 v152, v152, v145
	v_cvt_pk_bf16_f32 v148, v148, v148
	v_cvt_pk_bf16_f32 v152, v152, v152
	global_store_short v158, v148, s[2:3]
	global_store_short v158, v152, s[2:3] offset:64
	v_add_u32_e32 v157, 26, v162
	v_add_u32_e32 v158, 0x34000, v165
	v_cvt_f32_u32_e32 v157, v157
	v_fmamk_f32 v156, v157, 0xbcc4df2d, v160
	v_mul_f32_e64 v148, |v156|, v163
	v_mul_f32_e64 v152, |v156|, v164
	v_mul_f32_e32 v149, 0x3fb8aa3b, v148
	v_mul_f32_e32 v153, 0x3fb8aa3b, v152
	v_fma_f32 v150, v148, s22, -v149
	v_fma_f32 v154, v152, s22, -v153
	v_rndne_f32_e32 v151, v149
	v_rndne_f32_e32 v155, v153
	v_fmac_f32_e32 v150, 0x32a5705f, v148
	v_fmac_f32_e32 v154, 0x32a5705f, v152
	v_sub_f32_e32 v149, v149, v151
	v_sub_f32_e32 v153, v153, v155
	v_add_f32_e32 v149, v149, v150
	v_add_f32_e32 v153, v153, v154
	v_exp_f32_e32 v149, v149
	v_exp_f32_e32 v153, v153
	v_cvt_i32_f32_e32 v150, v151
	v_cvt_i32_f32_e32 v154, v155
	v_cmp_ngt_f32_e64 s[10:11], s23, v148
	v_cmp_ngt_f32_e64 s[18:19], s23, v152
	v_ldexp_f32 v149, v149, v150
	v_ldexp_f32 v153, v153, v154
	v_cndmask_b32_e64 v149, 0, v149, s[10:11]
	v_cndmask_b32_e64 v153, 0, v153, s[18:19]
	v_cmp_nlt_f32_e64 s[10:11], s24, v148
	v_cmp_nlt_f32_e64 s[18:19], s24, v152
	s_nop 1
	v_cndmask_b32_e64 v148, v161, v149, s[10:11]
	v_cndmask_b32_e64 v152, v161, v153, s[18:19]
	v_mul_f32_e32 v148, v148, v118
	v_mul_f32_e32 v152, v152, v146
	v_cvt_pk_bf16_f32 v148, v148, v148
	v_cvt_pk_bf16_f32 v152, v152, v152
	global_store_short v158, v148, s[2:3]
	global_store_short v158, v152, s[2:3] offset:64
	v_add_u32_e32 v157, 27, v162
	v_add_u32_e32 v158, 0x36000, v165
	v_cvt_f32_u32_e32 v157, v157
	v_fmamk_f32 v156, v157, 0xbcc4df2d, v160
	v_mul_f32_e64 v148, |v156|, v163
	v_mul_f32_e64 v152, |v156|, v164
	v_mul_f32_e32 v149, 0x3fb8aa3b, v148
	v_mul_f32_e32 v153, 0x3fb8aa3b, v152
	v_fma_f32 v150, v148, s22, -v149
	v_fma_f32 v154, v152, s22, -v153
	v_rndne_f32_e32 v151, v149
	v_rndne_f32_e32 v155, v153
	v_fmac_f32_e32 v150, 0x32a5705f, v148
	v_fmac_f32_e32 v154, 0x32a5705f, v152
	v_sub_f32_e32 v149, v149, v151
	v_sub_f32_e32 v153, v153, v155
	v_add_f32_e32 v149, v149, v150
	v_add_f32_e32 v153, v153, v154
	v_exp_f32_e32 v149, v149
	v_exp_f32_e32 v153, v153
	v_cvt_i32_f32_e32 v150, v151
	v_cvt_i32_f32_e32 v154, v155
	v_cmp_ngt_f32_e64 s[10:11], s23, v148
	v_cmp_ngt_f32_e64 s[18:19], s23, v152
	v_ldexp_f32 v149, v149, v150
	v_ldexp_f32 v153, v153, v154
	v_cndmask_b32_e64 v149, 0, v149, s[10:11]
	v_cndmask_b32_e64 v153, 0, v153, s[18:19]
	v_cmp_nlt_f32_e64 s[10:11], s24, v148
	v_cmp_nlt_f32_e64 s[18:19], s24, v152
	s_nop 1
	v_cndmask_b32_e64 v148, v161, v149, s[10:11]
	v_cndmask_b32_e64 v152, v161, v153, s[18:19]
	v_mul_f32_e32 v148, v148, v119
	v_mul_f32_e32 v152, v152, v147
	v_cvt_pk_bf16_f32 v148, v148, v148
	v_cvt_pk_bf16_f32 v152, v152, v152
	global_store_short v158, v148, s[2:3]
	global_store_short v158, v152, s[2:3] offset:64
	s_mov_b64 s[8:9], 0
